# gdn final stage hand-written, padded so all later code keeps its previous addresses
# speedup vs baseline: 1.0103x; 1.0024x over previous
; __device__ __forceinline__ float bf2f(bf16_t b) { return __uint_as_float((unsigned)b << 16); }
; __device__ __forceinline__ bf16_t f2bf(float f) { return (bf16_t)(pk2(f, 0.f) & 0xffffu); }
; __device__ __forceinline__ float fexp(float x) { return __expf(x); }
; __device__ __forceinline__ void gdn_unit(const Ctx& X, LAS unsigned char* hl, int b, int c, int h, int tid_h, int w4, int lane, int layer) {
;     ...
;     {
;         f32x4 acc[4];
;         const float eG63 = fexp(Gs[63]);
; #pragma unroll
;         for (int ct = 0; ct < 4; ++ct) acc[ct] = mma16(P, 16 * w4, WT, 16 * ct, (f32x4){0.f, 0.f, 0.f, 0.f}, r, q);
;         bf16_t* qe = WSP(bf16_t, WS_QEFF) + (size_t)uid * 4096;
; #pragma unroll
;         for (int ct = 0; ct < 4; ++ct)
; #pragma unroll
;             for (int j = 0; j < 4; ++j) { const int ii = 16 * w4 + 4 * q + j, col = 16 * ct + r;
;                 qe[ii * 64 + col] = f2bf(bf2f(Q[ii * LT + col]) * fexp(Gs[ii]) - acc[ct][j]); }
; #pragma unroll
;         for (int ct = 0; ct < 4; ++ct) acc[ct] = mma16(P, 16 * w4, UT, 16 * ct, (f32x4){0.f, 0.f, 0.f, 0.f}, r, q);
;         store_oloc(WSP(bf16_t, WS_OLOC), uid, w4, lane, acc);
; #pragma unroll
;         for (int ct = 0; ct < 4; ++ct) acc[ct] = mma16(KDT, 16 * w4, WT, 16 * ct, (f32x4){0.f, 0.f, 0.f, 0.f}, r, q);
;         bf16_t* mm = WSP(bf16_t, WS_MM) + (size_t)(uid - 2048) * 4096;
; #pragma unroll
;         for (int ct = 0; ct < 4; ++ct)
; #pragma unroll
;             for (int j = 0; j < 4; ++j) { const int ii = 16 * w4 + 4 * q + j, col = 16 * ct + r;
;                 mm[((w4 * 2 + (ct >> 1)) * 64 + (r >> 2) * 16 + 4 * q + j) * 8 + (ct & 1) * 4 + (r & 3)] = f2bf((ii == col ? eG63 : 0.f) - acc[ct][j]); }
; #pragma unroll
;         for (int ct = 0; ct < 4; ++ct) acc[ct] = mma16(KDT, 16 * w4, UT, 16 * ct, (f32x4){0.f, 0.f, 0.f, 0.f}, r, q);
;         store_bc(WSP(bf16_t, WS_BCS), uid, w4, r, q, acc);
;     }
.LBB0_619:
	s_waitcnt lgkmcnt(0)
	s_barrier
	v_bfe_u32 v54, v224, 6, 2
	v_and_b32_e32 v55, 15, v232
	v_lshrrev_b32_e32 v56, 4, v232
	v_lshl_or_b32 v57, v54, 4, v55
	v_mul_u32_u24_e32 v58, 0x90, v57
	v_mul_u32_u24_e32 v59, 0x90, v55
	v_lshl_add_u32 v60, v56, 4, v58
	v_lshl_add_u32 v61, v56, 4, v59
	v_add_u32_e32 v60, v182, v60
	v_add_u32_e32 v61, v182, v61
	v_add_u32_e32 v178, 0xb400, v60
	v_add_u32_e32 v179, 0x4800, v61
	v_add_u32_e32 v60, 0x9000, v60
	v_add_u32_e32 v61, 0x6c00, v61
	ds_read_b128 v[6:9], v178
	ds_read_b128 v[10:13], v178 offset:64
	ds_read_b128 v[22:25], v179
	ds_read_b128 v[26:29], v179 offset:64
	ds_read_b128 v[30:33], v179 offset:2304
	ds_read_b128 v[34:37], v179 offset:2368
	ds_read_b128 v[38:41], v179 offset:4608
	ds_read_b128 v[42:45], v179 offset:4672
	ds_read_b128 v[46:49], v179 offset:6912
	ds_read_b128 v[50:53], v179 offset:6976
	ds_read_b128 v[14:17], v60
	ds_read_b128 v[18:21], v60 offset:64
	v_lshl_add_u32 v62, v57, 2, v185
	v_lshl_add_u32 v63, v56, 3, v58
	v_add_u32_e32 v63, v182, v63
	ds_read_b32 v176, v62
	ds_read_b32 v177, v185 offset:252
	s_lshl_b32 s0, s22, 9
	s_lshl_b32 s1, s23, 7
	s_add_i32 s1, s1, s0
	s_or_b32 s0, s1, s21
	s_ashr_i32 s1, s0, 31
	s_lshl_b64 s[0:1], s[0:1], 13
	s_add_u32 s4, s89, s0
	s_addc_u32 s5, s78, s1
	s_add_u32 s6, s79, s0
	s_addc_u32 s7, s80, s1
	v_readlane_b32 s98, v253, 3
	v_readlane_b32 s99, v253, 4
	s_add_u32 s98, s98, s0
	s_addc_u32 s99, s99, s1
	s_add_u32 s98, s98, 0xff000000
	s_addc_u32 s99, s99, -1
	s_add_u32 s100, s74, s0
	s_addc_u32 s101, s75, s1
	v_readfirstlane_b32 s32, v54
	v_lshlrev_b32_e32 v64, 11, v54
	v_lshlrev_b32_e32 v65, 5, v232
	v_lshl_add_u32 v64, v232, 4, v64
	v_lshlrev_b32_e32 v66, 9, v54
	v_lshl_add_u32 v66, v232, 3, v66
	v_add_u32_e32 v67, 0x1000, v66
	v_lshlrev_b32_e32 v71, 7, v57
	v_lshl_add_u32 v71, v56, 3, v71
	v_lshlrev_b32_e32 v70, 2, v56
	v_sub_u32_e32 v70, v55, v70
	s_waitcnt lgkmcnt(4)
	v_mfma_f32_16x16x32_bf16 v[134:137], v[22:25], v[6:9], 0
	v_mfma_f32_16x16x32_bf16 v[138:141], v[30:33], v[6:9], 0
	v_mfma_f32_16x16x32_bf16 v[142:145], v[38:41], v[6:9], 0
	v_mfma_f32_16x16x32_bf16 v[146:149], v[46:49], v[6:9], 0
	v_mfma_f32_16x16x32_bf16 v[134:137], v[26:29], v[10:13], v[134:137]
	v_mfma_f32_16x16x32_bf16 v[138:141], v[34:37], v[10:13], v[138:141]
	v_mfma_f32_16x16x32_bf16 v[142:145], v[42:45], v[10:13], v[142:145]
	v_mfma_f32_16x16x32_bf16 v[146:149], v[50:53], v[10:13], v[146:149]
	ds_read_b64 v[150:151], v63
	ds_read_b64 v[152:153], v63 offset:32
	ds_read_b64 v[172:173], v63 offset:64
	ds_read_b64 v[174:175], v63 offset:96
	ds_read_b128 v[186:189], v61
	ds_read_b128 v[190:193], v61 offset:64
	ds_read_b128 v[194:197], v61 offset:2304
	ds_read_b128 v[198:201], v61 offset:2368
	ds_read_b128 v[202:205], v61 offset:4608
	ds_read_b128 v[206:209], v61 offset:4672
	ds_read_b128 v[210:213], v61 offset:6912
	s_waitcnt lgkmcnt(13)
	v_mfma_f32_16x16x32_bf16 v[236:239], v[22:25], v[14:17], 0
	v_mfma_f32_16x16x32_bf16 v[240:243], v[30:33], v[14:17], 0
	v_mfma_f32_16x16x32_bf16 v[244:247], v[38:41], v[14:17], 0
	v_mfma_f32_16x16x32_bf16 v[248:251], v[46:49], v[14:17], 0
	v_mfma_f32_16x16x32_bf16 v[236:239], v[26:29], v[18:21], v[236:239]
	v_mfma_f32_16x16x32_bf16 v[240:243], v[34:37], v[18:21], v[240:243]
	v_mfma_f32_16x16x32_bf16 v[244:247], v[42:45], v[18:21], v[244:247]
	v_mfma_f32_16x16x32_bf16 v[248:251], v[50:53], v[18:21], v[248:251]
	ds_read_b128 v[214:217], v61 offset:6976
	s_waitcnt lgkmcnt(8)
	v_mul_f32_e32 v176, 0x3fb8aa3b, v176
	v_mul_f32_e32 v177, 0x3fb8aa3b, v177
	v_exp_f32_e32 v176, v176
	v_exp_f32_e32 v177, v177
	v_cmp_eq_u32_e32 vcc, 0, v70
	v_cmp_eq_u32_e64 s[0:1], 1, v70
	v_cmp_eq_u32_e64 s[82:83], 2, v70
	v_cmp_eq_u32_e64 s[94:95], 3, v70
	s_waitcnt lgkmcnt(0)
	v_mfma_f32_16x16x32_bf16 v[84:87], v[6:9], v[186:189], 0
	v_mfma_f32_16x16x32_bf16 v[88:91], v[6:9], v[194:197], 0
	v_mfma_f32_16x16x32_bf16 v[92:95], v[6:9], v[202:205], 0
	v_mfma_f32_16x16x32_bf16 v[96:99], v[6:9], v[210:213], 0
	v_mfma_f32_16x16x32_bf16 v[114:117], v[14:17], v[186:189], 0
	v_mfma_f32_16x16x32_bf16 v[118:121], v[14:17], v[194:197], 0
	v_mfma_f32_16x16x32_bf16 v[122:125], v[14:17], v[202:205], 0
	v_mfma_f32_16x16x32_bf16 v[126:129], v[14:17], v[210:213], 0
	v_mfma_f32_16x16x32_bf16 v[84:87], v[10:13], v[190:193], v[84:87]
	v_mfma_f32_16x16x32_bf16 v[88:91], v[10:13], v[198:201], v[88:91]
	v_mfma_f32_16x16x32_bf16 v[92:95], v[10:13], v[206:209], v[92:95]
	v_mfma_f32_16x16x32_bf16 v[96:99], v[10:13], v[214:217], v[96:99]
	v_mfma_f32_16x16x32_bf16 v[114:117], v[18:21], v[190:193], v[114:117]
	v_mfma_f32_16x16x32_bf16 v[118:121], v[18:21], v[198:201], v[118:121]
	v_mfma_f32_16x16x32_bf16 v[122:125], v[18:21], v[206:209], v[122:125]
	v_mfma_f32_16x16x32_bf16 v[126:129], v[18:21], v[214:217], v[126:129]
	v_cndmask_b32_e32 v72, 0, v177, vcc
	v_cndmask_b32_e64 v73, 0, v177, s[0:1]
	v_cndmask_b32_e64 v74, 0, v177, s[82:83]
	v_cndmask_b32_e64 v75, 0, v177, s[94:95]
	v_lshlrev_b32_e32 v76, 16, v150
	v_and_b32_e32 v77, 0xffff0000, v150
	v_lshlrev_b32_e32 v78, 16, v151
	v_and_b32_e32 v79, 0xffff0000, v151
	v_fma_f32 v76, v176, v76, -v134
	v_fma_f32 v77, v176, v77, -v135
	v_fma_f32 v78, v176, v78, -v136
	v_fma_f32 v79, v176, v79, -v137
	v_cvt_pk_bf16_f32 v218, v76, v77
	v_cvt_pk_bf16_f32 v219, v78, v79
	global_store_dwordx2 v71, v[218:219], s[4:5]
	v_lshlrev_b32_e32 v76, 16, v152
	v_and_b32_e32 v77, 0xffff0000, v152
	v_lshlrev_b32_e32 v78, 16, v153
	v_and_b32_e32 v79, 0xffff0000, v153
	v_fma_f32 v76, v176, v76, -v138
	v_fma_f32 v77, v176, v77, -v139
	v_fma_f32 v78, v176, v78, -v140
	v_fma_f32 v79, v176, v79, -v141
	v_cvt_pk_bf16_f32 v220, v76, v77
	v_cvt_pk_bf16_f32 v221, v78, v79
; __device__ __forceinline__ float bf2f(bf16_t b) { return __uint_as_float((unsigned)b << 16); }
; __device__ __forceinline__ bf16_t f2bf(float f) { return (bf16_t)(pk2(f, 0.f) & 0xffffu); }
; __device__ __forceinline__ float fexp(float x) { return __expf(x); }
; #define LBAR() do { asm volatile("s_waitcnt lgkmcnt(0)" ::: "memory"); __builtin_amdgcn_s_barrier(); asm volatile("" ::: "memory"); } while (0)
; __device__ __forceinline__ void gdn_unit(const Ctx& X, LAS unsigned char* hl, int b, int c, int h, int tid_h, int w4, int lane, int layer) {
;     ...
;         bf16_t* qe = WSP(bf16_t, WS_QEFF) + (size_t)uid * 4096;
; #pragma unroll
;         for (int ct = 0; ct < 4; ++ct)
; #pragma unroll
;             for (int j = 0; j < 4; ++j) { const int ii = 16 * w4 + 4 * q + j, col = 16 * ct + r;
;                 qe[ii * 64 + col] = f2bf(bf2f(Q[ii * LT + col]) * fexp(Gs[ii]) - acc[ct][j]); }
; #pragma unroll
;         for (int ct = 0; ct < 4; ++ct) acc[ct] = mma16(P, 16 * w4, UT, 16 * ct, (f32x4){0.f, 0.f, 0.f, 0.f}, r, q);
;         store_oloc(WSP(bf16_t, WS_OLOC), uid, w4, lane, acc);
; #pragma unroll
;         for (int ct = 0; ct < 4; ++ct) acc[ct] = mma16(KDT, 16 * w4, WT, 16 * ct, (f32x4){0.f, 0.f, 0.f, 0.f}, r, q);
;         bf16_t* mm = WSP(bf16_t, WS_MM) + (size_t)(uid - 2048) * 4096;
; #pragma unroll
;         for (int ct = 0; ct < 4; ++ct)
; #pragma unroll
;             for (int j = 0; j < 4; ++j) { const int ii = 16 * w4 + 4 * q + j, col = 16 * ct + r;
;                 mm[((w4 * 2 + (ct >> 1)) * 64 + (r >> 2) * 16 + 4 * q + j) * 8 + (ct & 1) * 4 + (r & 3)] = f2bf((ii == col ? eG63 : 0.f) - acc[ct][j]); }
; #pragma unroll
;         for (int ct = 0; ct < 4; ++ct) acc[ct] = mma16(KDT, 16 * w4, UT, 16 * ct, (f32x4){0.f, 0.f, 0.f, 0.f}, r, q);
;         store_bc(WSP(bf16_t, WS_BCS), uid, w4, r, q, acc);
;     }
;     LBAR();
	global_store_dwordx2 v71, v[220:221], s[4:5] offset:32
	v_lshlrev_b32_e32 v76, 16, v172
	v_and_b32_e32 v77, 0xffff0000, v172
	v_lshlrev_b32_e32 v78, 16, v173
	v_and_b32_e32 v79, 0xffff0000, v173
	v_fma_f32 v76, v176, v76, -v142
	v_fma_f32 v77, v176, v77, -v143
	v_fma_f32 v78, v176, v78, -v144
	v_fma_f32 v79, v176, v79, -v145
	v_cvt_pk_bf16_f32 v222, v76, v77
	v_cvt_pk_bf16_f32 v223, v78, v79
	global_store_dwordx2 v71, v[222:223], s[4:5] offset:64
	v_lshlrev_b32_e32 v76, 16, v174
	v_and_b32_e32 v77, 0xffff0000, v174
	v_lshlrev_b32_e32 v78, 16, v175
	v_and_b32_e32 v79, 0xffff0000, v175
	v_fma_f32 v76, v176, v76, -v146
	v_fma_f32 v77, v176, v77, -v147
	v_fma_f32 v78, v176, v78, -v148
	v_fma_f32 v79, v176, v79, -v149
	v_cvt_pk_bf16_f32 v226, v76, v77
	v_cvt_pk_bf16_f32 v227, v78, v79
	global_store_dwordx2 v71, v[226:227], s[4:5] offset:96
	s_cmp_eq_u32 s32, 0
	s_cselect_b32 s0, 1.0, 0
	v_fma_f32 v76, v72, s0, -v236
	v_fma_f32 v77, v73, s0, -v237
	v_fma_f32 v78, v74, s0, -v238
	v_fma_f32 v79, v75, s0, -v239
	v_cvt_pk_bf16_f32 v100, v76, v77
	v_cvt_pk_bf16_f32 v101, v78, v79
	s_cmp_eq_u32 s32, 1
	s_cselect_b32 s0, 1.0, 0
	v_fma_f32 v76, v72, s0, -v240
	v_fma_f32 v77, v73, s0, -v241
	v_fma_f32 v78, v74, s0, -v242
	v_fma_f32 v79, v75, s0, -v243
	v_cvt_pk_bf16_f32 v102, v76, v77
	v_cvt_pk_bf16_f32 v103, v78, v79
	global_store_dwordx4 v64, v[100:103], s[98:99]
	s_cmp_eq_u32 s32, 2
	s_cselect_b32 s0, 1.0, 0
	v_fma_f32 v76, v72, s0, -v244
	v_fma_f32 v77, v73, s0, -v245
	v_fma_f32 v78, v74, s0, -v246
	v_fma_f32 v79, v75, s0, -v247
	v_cvt_pk_bf16_f32 v104, v76, v77
	v_cvt_pk_bf16_f32 v105, v78, v79
	s_cmp_eq_u32 s32, 3
	s_cselect_b32 s0, 1.0, 0
	v_fma_f32 v76, v72, s0, -v248
	v_fma_f32 v77, v73, s0, -v249
	v_fma_f32 v78, v74, s0, -v250
	v_fma_f32 v79, v75, s0, -v251
	v_cvt_pk_bf16_f32 v106, v76, v77
	v_cvt_pk_bf16_f32 v107, v78, v79
	global_store_dwordx4 v64, v[104:107], s[98:99] offset:1024
	v_cvt_pk_bf16_f32 v108, v84, v85
	v_cvt_pk_bf16_f32 v109, v86, v87
	v_cvt_pk_bf16_f32 v110, v88, v89
	v_cvt_pk_bf16_f32 v111, v90, v91
	global_store_dwordx4 v65, v[108:111], s[6:7] nt
	v_cvt_pk_bf16_f32 v80, v92, v93
	v_cvt_pk_bf16_f32 v81, v94, v95
	v_cvt_pk_bf16_f32 v82, v96, v97
	v_cvt_pk_bf16_f32 v83, v98, v99
	global_store_dwordx4 v65, v[80:83], s[6:7] offset:16 nt
	v_cvt_pk_bf16_f32 v40, v114, v115
	v_cvt_pk_bf16_f32 v41, v116, v117
	global_store_dwordx2 v66, v[40:41], s[100:101]
	v_cvt_pk_bf16_f32 v42, v118, v119
	v_cvt_pk_bf16_f32 v43, v120, v121
	global_store_dwordx2 v66, v[42:43], s[100:101] offset:2048
	v_cvt_pk_bf16_f32 v44, v122, v123
	v_cvt_pk_bf16_f32 v45, v124, v125
	global_store_dwordx2 v67, v[44:45], s[100:101]
	v_cvt_pk_bf16_f32 v46, v126, v127
	v_cvt_pk_bf16_f32 v47, v128, v129
	global_store_dwordx2 v67, v[46:47], s[100:101] offset:2048
	s_branch .Lgdn_p4_pad_end
	s_nop 0
	s_nop 0
	s_nop 0
	s_nop 0
	s_nop 0
	s_nop 0
	s_nop 0
	s_nop 0
	s_nop 0
	s_nop 0
	s_nop 0
	s_nop 0
	s_nop 0
	s_nop 0
	s_nop 0
	s_nop 0
	s_nop 0
	s_nop 0
	s_nop 0
	s_nop 0
	s_nop 0
	s_nop 0
	s_nop 0
	s_nop 0
	s_nop 0
	s_nop 0
	s_nop 0
	s_nop 0
	s_nop 0
	s_nop 0
	s_nop 0
	s_nop 0
	s_nop 0
	s_nop 0
	s_nop 0
	s_nop 0
	s_nop 0
	s_nop 0
	s_nop 0
	s_nop 0
	s_nop 0
	s_nop 0
	s_nop 0
	s_nop 0
	s_nop 0
	s_nop 0
	s_nop 0
	s_nop 0
	s_nop 0
	s_nop 0
	s_nop 0
	s_nop 0
	s_nop 0
	s_nop 0
	s_nop 0
	s_nop 0
	s_nop 0
	s_nop 0
	s_nop 0
	s_nop 0
	s_nop 0
	s_nop 0
	s_nop 0
	s_nop 0
	s_nop 0
	s_nop 0
	s_nop 0
	s_nop 0
	s_nop 0
	s_nop 0
	s_nop 0
	s_nop 0
	s_nop 0
	s_nop 0
	s_nop 0
	s_nop 0
	s_nop 0
	s_nop 0
	s_nop 0
	s_nop 0
	s_nop 0
	s_nop 0
	s_nop 0
	s_nop 0
	s_nop 0
	s_nop 0
	s_nop 0
	s_nop 0
	s_nop 0
	s_nop 0
	s_nop 0
	s_nop 0
	s_nop 0
	s_nop 0
	s_nop 0
	s_nop 0
	s_nop 0
	s_nop 0
	s_nop 0
	s_nop 0
	s_nop 0
	s_nop 0
	s_nop 0
	s_nop 0
	s_nop 0
	s_nop 0
	s_nop 0
	s_nop 0
	s_nop 0
	s_nop 0
	s_nop 0
	s_nop 0
	s_nop 0
	s_nop 0
	s_nop 0
	s_nop 0
	s_nop 0
	s_nop 0
	s_nop 0
	s_nop 0
	s_nop 0
	s_nop 0
	s_nop 0
	s_nop 0
	s_nop 0
	s_nop 0
	s_nop 0
	s_nop 0
	s_nop 0
	s_nop 0
	s_nop 0
	s_nop 0
	s_nop 0
	s_nop 0
	s_nop 0
	s_nop 0
	s_nop 0
	s_nop 0
	s_nop 0
	s_nop 0
	s_nop 0
	s_nop 0
	s_nop 0
	s_nop 0
	s_nop 0
	s_nop 0
	s_nop 0
	s_nop 0
	s_nop 0
	s_nop 0
	s_nop 0
	s_nop 0
	s_nop 0
	s_nop 0
	s_nop 0
	s_nop 0
	s_nop 0
	s_nop 0
	s_nop 0
	s_nop 0
	s_nop 0
	s_nop 0
	s_nop 0
	s_nop 0
	s_nop 0
	s_nop 0
	s_nop 0
	s_nop 0
	s_nop 0
	s_nop 0
	s_nop 0
	s_nop 0
	s_nop 0
	s_nop 0
	s_nop 0
	s_nop 0
	s_nop 0
	s_nop 0
	s_nop 0
	s_nop 0
	s_nop 0
	s_nop 0
	s_nop 0
	s_nop 0
	s_nop 0
	s_nop 0
	s_nop 0
	s_nop 0
	s_nop 0
	s_nop 0
	s_nop 0
	s_nop 0
	s_nop 0
	s_nop 0
	s_nop 0
	s_nop 0
	s_nop 0
	s_nop 0
	s_nop 0
	s_nop 0
	s_nop 0
	s_nop 0
	s_nop 0
	s_nop 0
	s_nop 0
	s_nop 0
	s_nop 0
	s_nop 0
	s_nop 0
	s_nop 0
	s_nop 0
	s_nop 0
	s_nop 0
	s_nop 0
	s_nop 0
	s_nop 0
	s_nop 0
	s_nop 0
	s_nop 0
	s_nop 0
	s_nop 0
	s_nop 0
	s_nop 0
	s_nop 0
	s_nop 0
	s_nop 0
	s_nop 0
	s_nop 0
	s_nop 0
	s_nop 0
	s_nop 0
	s_nop 0
	s_nop 0
	s_nop 0
	s_nop 0
	s_nop 0
	s_nop 0
	s_nop 0
	s_nop 0
	s_nop 0
	s_nop 0
	s_nop 0
	s_nop 0
	s_nop 0
	s_nop 0
	s_nop 0
	s_nop 0
	s_nop 0
	s_nop 0
	s_nop 0
	s_nop 0
	s_nop 0
	s_nop 0
	s_nop 0
	s_nop 0
	s_nop 0
	s_nop 0
	s_nop 0
	s_nop 0
	s_nop 0
	s_nop 0
	s_nop 0
	s_nop 0
	s_nop 0
	s_nop 0
	s_nop 0
	s_nop 0
	s_nop 0
	s_nop 0
	s_nop 0
	s_nop 0
	s_nop 0
	s_nop 0
	s_nop 0
	s_nop 0
	s_nop 0
	s_nop 0
	s_nop 0
	s_nop 0
	s_nop 0
	s_nop 0
	s_nop 0
	s_nop 0
	s_nop 0
	s_nop 0
	s_nop 0
	s_nop 0
	s_nop 0
	s_nop 0
	s_nop 0
	s_nop 0
	s_nop 0
	s_nop 0
	s_nop 0
	s_nop 0
	s_nop 0
	s_nop 0
	s_nop 0
	s_nop 0
	s_nop 0
	s_nop 0
	s_nop 0
	s_nop 0
	s_nop 0
	s_nop 0
	s_nop 0
	s_nop 0
	s_nop 0
	s_nop 0
	s_nop 0
	s_nop 0
	s_nop 0
	s_nop 0
	s_nop 0
	s_nop 0
	s_nop 0
	s_nop 0
	s_nop 0
	s_nop 0
	s_nop 0
	s_nop 0
	s_nop 0
	s_nop 0
	s_nop 0
	s_nop 0
	s_nop 0
	s_nop 0
	s_nop 0
	s_nop 0
	s_nop 0
	s_nop 0
	s_nop 0
	s_nop 0
	s_nop 0
	s_nop 0
	s_nop 0
	s_nop 0
	s_nop 0
	s_nop 0
	s_nop 0
	s_nop 0
.Lgdn_p4_pad_end:
	s_waitcnt lgkmcnt(0)
	s_barrier
	s_mov_b64 s[0:1], 0
